# removed per-block s_setprio flips in the GU GEMM K-loop (timing only)
# baseline (speedup 1.0000x reference)
; #define PG8_STAGE(bufoff, gbase, voff) do { _Pragma("unroll") for (int _i = 0; _i < 2; ++_i) \
;         __builtin_amdgcn_global_load_lds((const unsigned*)((const char*)(gbase) + (voff)[_i]), (PG8_LAS unsigned*)(lds + (bufoff) + ldsw + _i * 8192), 16, 0, 0); } while (0)
; #define PG8_LDA(dst, b, h) do { _Pragma("unroll") for (int m = 0; m < 4; ++m) _Pragma("unroll") for (int k = 0; k < 2; ++k) dst[m][k] = *(const PG8_LAS bf16x8*)(lds + PG8_SA(b, h) + aoff + m * 2048 + k * 1024); } while (0)
; #define PG8_LDB(dst, b, h) do { _Pragma("unroll") for (int n = 0; n < 2; ++n) _Pragma("unroll") for (int k = 0; k < 2; ++k) dst[n][k] = *(const PG8_LAS bf16x8*)(lds + PG8_SB(b, h) + boff + n * 2048 + k * 1024); } while (0)
; #define PG8_MMA(ai, bj, At, Bt) do { __builtin_amdgcn_s_setprio(1); _Pragma("unroll") for (int m = 0; m < 4; ++m) _Pragma("unroll") for (int n = 0; n < 2; ++n) _Pragma("unroll") for (int k = 0; k < 2; ++k) \
;         acc[ai][bj][m][n] = __builtin_amdgcn_mfma_f32_16x16x32_bf16(Bt[n][k], At[m][k], acc[ai][bj][m][n], 0, 0, 0); __builtin_amdgcn_s_setprio(0); } while (0)
; #define PG8_WAIT_V(n) asm volatile("s_waitcnt vmcnt(" #n ")" ::: "memory")
; #define PG8_WAIT_L(n) asm volatile("s_waitcnt lgkmcnt(" #n ")" ::: "memory")
; #define PG8_BAR __builtin_amdgcn_s_barrier()
; #define PG8_SCHED __builtin_amdgcn_sched_barrier(0)
; template <class Epi, class Sched, bool ALIGN_EPI = false, bool SP2 = false>
; __device__ __forceinline__ void gemm_phase(PG8_LAS unsigned char* lds, const Gemm g, const Sched& S, const Epi& E) {
;     ...
;             PG8_LDB(B0, 0, 0); PG8_LDB(B1, 0, 1); PG8_SCHED; PG8_LDA(At, 0, 0); PG8_STAGE(PG8_SA(1, 1), a1 + hstep, voffA);
;             PG8_WAIT_V(8); PG8_WAIT_L(0); PG8_BAR; PG8_MMA(0, 0, At, B0); PG8_MMA(0, 1, At, B1); PG8_BAR; PG8_SCHED;
;             PG8_LDA(At, 0, 1); PG8_STAGE(PG8_SB(0, 0), b2, voffB); PG8_STAGE(PG8_SB(0, 1), b2 + hstep, voffB); PG8_STAGE(PG8_SA(0, 0), a2, voffA);
;             PG8_WAIT_V(8); PG8_WAIT_L(0); PG8_BAR; PG8_MMA(1, 0, At, B0); PG8_MMA(1, 1, At, B1); PG8_BAR; PG8_SCHED;
.LBB0_698:
	s_add_u32 s24, s22, 0xfffc0080
	s_addc_u32 s25, s23, -1
	s_add_i32 s46, 0, 0x10000
	s_cmp_eq_u32 s73, 12
	s_cselect_b32 s41, s15, s25
	s_cselect_b32 s40, s33, s24
	s_cselect_b32 s25, s17, s72
	s_cselect_b32 s24, s61, s71
	s_add_i32 s80, 0, 0x14000
	v_add_u32_e32 v142, s46, v163
	v_add_u32_e32 v182, s80, v163
	ds_read_b128 v[0:3], v142
	ds_read_b128 v[4:7], v142 offset:1024
	ds_read_b128 v[138:141], v142 offset:2048
	ds_read_b128 v[142:145], v142 offset:3072
	ds_read_b128 v[146:149], v182
	ds_read_b128 v[150:153], v182 offset:1024
	ds_read_b128 v[178:181], v182 offset:2048
	ds_read_b128 v[182:185], v182 offset:3072
	v_lshl_add_u64 v[186:187], s[22:23], 0, v[174:175]
	s_add_i32 m0, s53, 0xc000
	ds_read_b128 v[190:193], v189
	ds_read_b128 v[194:197], v189 offset:1024
	ds_read_b128 v[210:213], v189 offset:2048
	ds_read_b128 v[214:217], v189 offset:3072
	ds_read_b128 v[218:221], v189 offset:4096
	ds_read_b128 v[222:225], v189 offset:5120
	ds_read_b128 v[226:229], v189 offset:6144
	ds_read_b128 v[230:233], v189 offset:7168
	global_load_lds_dwordx4 v[186:187], off
	v_lshl_add_u64 v[186:187], s[22:23], 0, v[176:177]
	s_add_i32 m0, s53, 0xe000
	s_nop 0
	global_load_lds_dwordx4 v[186:187], off
	s_waitcnt vmcnt(8)
	s_waitcnt lgkmcnt(0)
	s_barrier
	s_waitcnt lgkmcnt(0)
	v_mfma_f32_16x16x32_bf16 v[134:137], v[0:3], v[190:193], v[134:137]
	v_mfma_f32_16x16x32_bf16 v[126:129], v[138:141], v[190:193], v[126:129]
	v_mfma_f32_16x16x32_bf16 v[118:121], v[0:3], v[210:213], v[118:121]
	v_mfma_f32_16x16x32_bf16 v[110:113], v[138:141], v[210:213], v[110:113]
	v_mfma_f32_16x16x32_bf16 v[102:105], v[0:3], v[218:221], v[102:105]
	v_mfma_f32_16x16x32_bf16 v[94:97], v[138:141], v[218:221], v[94:97]
	v_mfma_f32_16x16x32_bf16 v[86:89], v[0:3], v[226:229], v[86:89]
	v_mfma_f32_16x16x32_bf16 v[78:81], v[138:141], v[226:229], v[78:81]
	v_mfma_f32_16x16x32_bf16 v[134:137], v[4:7], v[194:197], v[134:137]
	v_mfma_f32_16x16x32_bf16 v[126:129], v[142:145], v[194:197], v[126:129]
	v_mfma_f32_16x16x32_bf16 v[118:121], v[4:7], v[214:217], v[118:121]
	v_mfma_f32_16x16x32_bf16 v[110:113], v[142:145], v[214:217], v[110:113]
	v_mfma_f32_16x16x32_bf16 v[102:105], v[4:7], v[222:225], v[102:105]
	v_mfma_f32_16x16x32_bf16 v[94:97], v[142:145], v[222:225], v[94:97]
	v_mfma_f32_16x16x32_bf16 v[86:89], v[4:7], v[230:233], v[86:89]
	v_mfma_f32_16x16x32_bf16 v[78:81], v[142:145], v[230:233], v[78:81]
	v_mfma_f32_16x16x32_bf16 v[130:133], v[146:149], v[190:193], v[130:133]
	v_mfma_f32_16x16x32_bf16 v[122:125], v[178:181], v[190:193], v[122:125]
	v_mfma_f32_16x16x32_bf16 v[114:117], v[146:149], v[210:213], v[114:117]
	v_mfma_f32_16x16x32_bf16 v[106:109], v[178:181], v[210:213], v[106:109]
	v_mfma_f32_16x16x32_bf16 v[98:101], v[146:149], v[218:221], v[98:101]
	v_mfma_f32_16x16x32_bf16 v[90:93], v[178:181], v[218:221], v[90:93]
	v_mfma_f32_16x16x32_bf16 v[82:85], v[146:149], v[226:229], v[82:85]
	v_mfma_f32_16x16x32_bf16 v[74:77], v[178:181], v[226:229], v[74:77]
	v_mfma_f32_16x16x32_bf16 v[130:133], v[150:153], v[194:197], v[130:133]
	v_mfma_f32_16x16x32_bf16 v[122:125], v[182:185], v[194:197], v[122:125]
	v_mfma_f32_16x16x32_bf16 v[114:117], v[150:153], v[214:217], v[114:117]
	v_mfma_f32_16x16x32_bf16 v[106:109], v[182:185], v[214:217], v[106:109]
	v_mfma_f32_16x16x32_bf16 v[98:101], v[150:153], v[222:225], v[98:101]
	v_mfma_f32_16x16x32_bf16 v[90:93], v[182:185], v[222:225], v[90:93]
	v_mfma_f32_16x16x32_bf16 v[82:85], v[150:153], v[230:233], v[82:85]
	v_mfma_f32_16x16x32_bf16 v[74:77], v[182:185], v[230:233], v[74:77]
	s_barrier
	s_add_i32 s46, s46, s52
	v_lshl_add_u64 v[186:187], s[24:25], 0, v[170:171]
	s_mov_b32 m0, s46
	ds_read_b128 v[190:193], v189 offset:16384
	ds_read_b128 v[194:197], v189 offset:17408
	ds_read_b128 v[210:213], v189 offset:18432
	ds_read_b128 v[214:217], v189 offset:19456
	ds_read_b128 v[218:221], v189 offset:20480
	ds_read_b128 v[222:225], v189 offset:21504
	ds_read_b128 v[226:229], v189 offset:22528
	ds_read_b128 v[230:233], v189 offset:23552
	global_load_lds_dwordx4 v[186:187], off
	s_add_i32 m0, s46, 0x2000
	s_add_u32 s46, s24, 0x40000
	v_lshl_add_u64 v[198:199], s[24:25], 0, v[154:155]
	s_addc_u32 s47, s25, 0
	s_add_i32 s80, s80, s52
	global_load_lds_dwordx4 v[198:199], off
	v_lshl_add_u64 v[234:235], s[46:47], 0, v[170:171]
	s_mov_b32 m0, s80
	v_lshl_add_u64 v[236:237], s[40:41], 0, v[156:157]
	global_load_lds_dwordx4 v[234:235], off
	v_lshl_add_u64 v[234:235], s[46:47], 0, v[154:155]
	s_add_i32 m0, s80, 0x2000
	s_nop 0
	global_load_lds_dwordx4 v[234:235], off
	v_lshl_add_u64 v[234:235], s[40:41], 0, v[172:173]
	s_waitcnt vmcnt(6)
	s_waitcnt lgkmcnt(0)
	s_barrier
; #define PG8_STAGE(bufoff, gbase, voff) do { _Pragma("unroll") for (int _i = 0; _i < 2; ++_i) \
;         __builtin_amdgcn_global_load_lds((const unsigned*)((const char*)(gbase) + (voff)[_i]), (PG8_LAS unsigned*)(lds + (bufoff) + ldsw + _i * 8192), 16, 0, 0); } while (0)
; #define PG8_LDA(dst, b, h) do { _Pragma("unroll") for (int m = 0; m < 4; ++m) _Pragma("unroll") for (int k = 0; k < 2; ++k) dst[m][k] = *(const PG8_LAS bf16x8*)(lds + PG8_SA(b, h) + aoff + m * 2048 + k * 1024); } while (0)
; #define PG8_LDB(dst, b, h) do { _Pragma("unroll") for (int n = 0; n < 2; ++n) _Pragma("unroll") for (int k = 0; k < 2; ++k) dst[n][k] = *(const PG8_LAS bf16x8*)(lds + PG8_SB(b, h) + boff + n * 2048 + k * 1024); } while (0)
; #define PG8_MMA(ai, bj, At, Bt) do { __builtin_amdgcn_s_setprio(1); _Pragma("unroll") for (int m = 0; m < 4; ++m) _Pragma("unroll") for (int n = 0; n < 2; ++n) _Pragma("unroll") for (int k = 0; k < 2; ++k) \
;         acc[ai][bj][m][n] = __builtin_amdgcn_mfma_f32_16x16x32_bf16(Bt[n][k], At[m][k], acc[ai][bj][m][n], 0, 0, 0); __builtin_amdgcn_s_setprio(0); } while (0)
; #define PG8_WAIT_V(n) asm volatile("s_waitcnt vmcnt(" #n ")" ::: "memory")
; #define PG8_WAIT_L(n) asm volatile("s_waitcnt lgkmcnt(" #n ")" ::: "memory")
; #define PG8_BAR __builtin_amdgcn_s_barrier()
; #define PG8_SCHED __builtin_amdgcn_sched_barrier(0)
; template <class Epi, class Sched, bool ALIGN_EPI = false, bool SP2 = false>
; __device__ __forceinline__ void gemm_phase(PG8_LAS unsigned char* lds, const Gemm g, const Sched& S, const Epi& E) {
;     ...
;             PG8_WAIT_V(8); PG8_WAIT_L(0); PG8_BAR; PG8_MMA(1, 0, At, B0); PG8_MMA(1, 1, At, B1); PG8_BAR; PG8_SCHED;
;             PG8_LDB(B0, 1, 0); PG8_LDB(B1, 1, 1); PG8_SCHED; PG8_LDA(At, 1, 0); PG8_STAGE(PG8_SA(0, 1), a2 + hstep, voffA);
;             PG8_WAIT_V(8); PG8_WAIT_L(0); PG8_BAR; PG8_MMA(0, 0, At, B0); PG8_MMA(0, 1, At, B1); PG8_BAR; PG8_SCHED;
	s_waitcnt lgkmcnt(0)
	v_mfma_f32_16x16x32_bf16 v[70:73], v[0:3], v[190:193], v[70:73]
	v_mfma_f32_16x16x32_bf16 v[62:65], v[138:141], v[190:193], v[62:65]
	v_mfma_f32_16x16x32_bf16 v[54:57], v[0:3], v[210:213], v[54:57]
	v_mfma_f32_16x16x32_bf16 v[46:49], v[138:141], v[210:213], v[46:49]
	v_mfma_f32_16x16x32_bf16 v[38:41], v[0:3], v[218:221], v[38:41]
	v_mfma_f32_16x16x32_bf16 v[30:33], v[138:141], v[218:221], v[30:33]
	v_mfma_f32_16x16x32_bf16 v[0:3], v[0:3], v[226:229], v[22:25]
	s_mov_b32 m0, s53
	v_mfma_f32_16x16x32_bf16 v[70:73], v[4:7], v[194:197], v[70:73]
	global_load_lds_dwordx4 v[234:235], off
	v_mfma_f32_16x16x32_bf16 v[62:65], v[142:145], v[194:197], v[62:65]
	v_mfma_f32_16x16x32_bf16 v[54:57], v[4:7], v[214:217], v[54:57]
	v_mfma_f32_16x16x32_bf16 v[46:49], v[142:145], v[214:217], v[46:49]
	v_mfma_f32_16x16x32_bf16 v[38:41], v[4:7], v[222:225], v[38:41]
	v_mfma_f32_16x16x32_bf16 v[30:33], v[142:145], v[222:225], v[30:33]
	v_mfma_f32_16x16x32_bf16 v[0:3], v[4:7], v[230:233], v[0:3]
	v_mfma_f32_16x16x32_bf16 v[4:7], v[138:141], v[226:229], v[14:17]
	v_mfma_f32_16x16x32_bf16 v[4:7], v[142:145], v[230:233], v[4:7]
	v_mfma_f32_16x16x32_bf16 v[14:17], v[146:149], v[190:193], v[66:69]
	v_mfma_f32_16x16x32_bf16 v[66:69], v[150:153], v[194:197], v[14:17]
	v_mfma_f32_16x16x32_bf16 v[14:17], v[178:181], v[190:193], v[58:61]
	v_mfma_f32_16x16x32_bf16 v[58:61], v[182:185], v[194:197], v[14:17]
	v_mfma_f32_16x16x32_bf16 v[14:17], v[146:149], v[210:213], v[50:53]
	v_mfma_f32_16x16x32_bf16 v[50:53], v[150:153], v[214:217], v[14:17]
	v_mfma_f32_16x16x32_bf16 v[14:17], v[178:181], v[210:213], v[42:45]
	s_mov_b32 m0, s54
	v_mfma_f32_16x16x32_bf16 v[42:45], v[182:185], v[214:217], v[14:17]
	global_load_lds_dwordx4 v[236:237], off
	v_mfma_f32_16x16x32_bf16 v[14:17], v[146:149], v[218:221], v[34:37]
	v_mfma_f32_16x16x32_bf16 v[34:37], v[150:153], v[222:225], v[14:17]
	v_mfma_f32_16x16x32_bf16 v[14:17], v[178:181], v[218:221], v[26:29]
	v_mfma_f32_16x16x32_bf16 v[26:29], v[182:185], v[222:225], v[14:17]
	v_mfma_f32_16x16x32_bf16 v[14:17], v[146:149], v[226:229], v[18:21]
	v_mfma_f32_16x16x32_bf16 v[10:13], v[178:181], v[226:229], v[10:13]
	v_mfma_f32_16x16x32_bf16 v[18:21], v[150:153], v[230:233], v[14:17]
	v_mfma_f32_16x16x32_bf16 v[10:13], v[182:185], v[230:233], v[10:13]
	s_barrier
	s_add_i32 s46, 0, 0x18000
	s_add_i32 s47, 0, 0x1c000
	v_add_u32_e32 v142, s46, v163
	v_add_u32_e32 v182, s47, v163
	ds_read_b128 v[14:17], v142
	ds_read_b128 v[22:25], v142 offset:1024
	ds_read_b128 v[138:141], v142 offset:2048
	ds_read_b128 v[142:145], v142 offset:3072
	ds_read_b128 v[146:149], v182
	ds_read_b128 v[150:153], v182 offset:1024
	ds_read_b128 v[178:181], v182 offset:2048
	ds_read_b128 v[182:185], v182 offset:3072
	s_add_u32 s40, s40, 0x40000
	s_addc_u32 s41, s41, 0
	s_mov_b32 m0, s55
	v_lshl_add_u64 v[238:239], s[40:41], 0, v[172:173]
	ds_read_b128 v[190:193], v189 offset:32768
	ds_read_b128 v[194:197], v189 offset:33792
	ds_read_b128 v[210:213], v189 offset:34816
	ds_read_b128 v[214:217], v189 offset:35840
	ds_read_b128 v[218:221], v189 offset:36864
	ds_read_b128 v[222:225], v189 offset:37888
	ds_read_b128 v[226:229], v189 offset:38912
	ds_read_b128 v[230:233], v189 offset:39936
	global_load_lds_dwordx4 v[238:239], off
	v_lshl_add_u64 v[238:239], s[40:41], 0, v[156:157]
	s_mov_b32 m0, s56
	s_nop 0
	global_load_lds_dwordx4 v[238:239], off
	s_waitcnt vmcnt(8)
	s_waitcnt lgkmcnt(0)
	s_barrier
	s_waitcnt lgkmcnt(0)
	v_mfma_f32_16x16x32_bf16 v[134:137], v[14:17], v[190:193], v[134:137]
	v_mfma_f32_16x16x32_bf16 v[126:129], v[138:141], v[190:193], v[126:129]
	v_mfma_f32_16x16x32_bf16 v[118:121], v[14:17], v[210:213], v[118:121]
	v_mfma_f32_16x16x32_bf16 v[110:113], v[138:141], v[210:213], v[110:113]
	v_mfma_f32_16x16x32_bf16 v[102:105], v[14:17], v[218:221], v[102:105]
	v_mfma_f32_16x16x32_bf16 v[94:97], v[138:141], v[218:221], v[94:97]
	v_mfma_f32_16x16x32_bf16 v[86:89], v[14:17], v[226:229], v[86:89]
	v_mfma_f32_16x16x32_bf16 v[78:81], v[138:141], v[226:229], v[78:81]
	v_mfma_f32_16x16x32_bf16 v[134:137], v[22:25], v[194:197], v[134:137]
	v_mfma_f32_16x16x32_bf16 v[126:129], v[142:145], v[194:197], v[126:129]
	v_mfma_f32_16x16x32_bf16 v[118:121], v[22:25], v[214:217], v[118:121]
	v_mfma_f32_16x16x32_bf16 v[110:113], v[142:145], v[214:217], v[110:113]
	v_mfma_f32_16x16x32_bf16 v[102:105], v[22:25], v[222:225], v[102:105]
	v_mfma_f32_16x16x32_bf16 v[94:97], v[142:145], v[222:225], v[94:97]
	v_mfma_f32_16x16x32_bf16 v[86:89], v[22:25], v[230:233], v[86:89]
	v_mfma_f32_16x16x32_bf16 v[78:81], v[142:145], v[230:233], v[78:81]
	v_mfma_f32_16x16x32_bf16 v[130:133], v[146:149], v[190:193], v[130:133]
	v_mfma_f32_16x16x32_bf16 v[122:125], v[178:181], v[190:193], v[122:125]
	v_mfma_f32_16x16x32_bf16 v[114:117], v[146:149], v[210:213], v[114:117]
	v_mfma_f32_16x16x32_bf16 v[106:109], v[178:181], v[210:213], v[106:109]
	v_mfma_f32_16x16x32_bf16 v[98:101], v[146:149], v[218:221], v[98:101]
	v_mfma_f32_16x16x32_bf16 v[90:93], v[178:181], v[218:221], v[90:93]
	v_mfma_f32_16x16x32_bf16 v[82:85], v[146:149], v[226:229], v[82:85]
	v_mfma_f32_16x16x32_bf16 v[74:77], v[178:181], v[226:229], v[74:77]
	v_mfma_f32_16x16x32_bf16 v[130:133], v[150:153], v[194:197], v[130:133]
	v_mfma_f32_16x16x32_bf16 v[122:125], v[182:185], v[194:197], v[122:125]
	v_mfma_f32_16x16x32_bf16 v[114:117], v[150:153], v[214:217], v[114:117]
	v_mfma_f32_16x16x32_bf16 v[106:109], v[182:185], v[214:217], v[106:109]
	v_mfma_f32_16x16x32_bf16 v[98:101], v[150:153], v[222:225], v[98:101]
	v_mfma_f32_16x16x32_bf16 v[90:93], v[182:185], v[222:225], v[90:93]
	v_mfma_f32_16x16x32_bf16 v[82:85], v[150:153], v[230:233], v[82:85]
	v_mfma_f32_16x16x32_bf16 v[74:77], v[182:185], v[230:233], v[74:77]
	s_barrier
; #define PG8_STAGE(bufoff, gbase, voff) do { _Pragma("unroll") for (int _i = 0; _i < 2; ++_i) \
;         __builtin_amdgcn_global_load_lds((const unsigned*)((const char*)(gbase) + (voff)[_i]), (PG8_LAS unsigned*)(lds + (bufoff) + ldsw + _i * 8192), 16, 0, 0); } while (0)
; #define PG8_LDA(dst, b, h) do { _Pragma("unroll") for (int m = 0; m < 4; ++m) _Pragma("unroll") for (int k = 0; k < 2; ++k) dst[m][k] = *(const PG8_LAS bf16x8*)(lds + PG8_SA(b, h) + aoff + m * 2048 + k * 1024); } while (0)
; #define PG8_MMA(ai, bj, At, Bt) do { __builtin_amdgcn_s_setprio(1); _Pragma("unroll") for (int m = 0; m < 4; ++m) _Pragma("unroll") for (int n = 0; n < 2; ++n) _Pragma("unroll") for (int k = 0; k < 2; ++k) \
;         acc[ai][bj][m][n] = __builtin_amdgcn_mfma_f32_16x16x32_bf16(Bt[n][k], At[m][k], acc[ai][bj][m][n], 0, 0, 0); __builtin_amdgcn_s_setprio(0); } while (0)
; #define PG8_WAIT_V(n) asm volatile("s_waitcnt vmcnt(" #n ")" ::: "memory")
; #define PG8_WAIT_L(n) asm volatile("s_waitcnt lgkmcnt(" #n ")" ::: "memory")
; #define PG8_BAR __builtin_amdgcn_s_barrier()
; #define PG8_SCHED __builtin_amdgcn_sched_barrier(0)
; template <class Epi, class Sched, bool ALIGN_EPI = false, bool SP2 = false>
; __device__ __forceinline__ void gemm_phase(PG8_LAS unsigned char* lds, const Gemm g, const Sched& S, const Epi& E) {
;     ...
;             PG8_WAIT_V(8); PG8_WAIT_L(0); PG8_BAR; PG8_MMA(0, 0, At, B0); PG8_MMA(0, 1, At, B1); PG8_BAR; PG8_SCHED;
;             PG8_LDA(At, 1, 1); PG8_STAGE(PG8_SB(1, 0), b3, voffB); PG8_STAGE(PG8_SB(1, 1), b3 + hstep, voffB); PG8_STAGE(PG8_SA(1, 0), a3, voffA);
;             PG8_WAIT_V(8); PG8_WAIT_L(0); PG8_BAR; PG8_MMA(1, 0, At, B0); PG8_MMA(1, 1, At, B1); PG8_BAR; PG8_SCHED;
	s_add_i32 s40, s46, s52
	v_lshl_add_u64 v[186:187], v[186:187], 0, s[44:45]
	s_mov_b32 m0, s40
	ds_read_b128 v[190:193], v189 offset:49152
	ds_read_b128 v[194:197], v189 offset:50176
	ds_read_b128 v[210:213], v189 offset:51200
	ds_read_b128 v[214:217], v189 offset:52224
	ds_read_b128 v[218:221], v189 offset:53248
	ds_read_b128 v[222:225], v189 offset:54272
	ds_read_b128 v[226:229], v189 offset:55296
	ds_read_b128 v[230:233], v189 offset:56320
	global_load_lds_dwordx4 v[186:187], off
	s_add_i32 m0, s40, 0x2000
	s_add_u32 s24, s24, 0x40080
	v_lshl_add_u64 v[186:187], v[198:199], 0, s[44:45]
	s_addc_u32 s25, s25, 0
	s_add_i32 s40, s47, s52
	global_load_lds_dwordx4 v[186:187], off
	v_lshl_add_u64 v[186:187], s[24:25], 0, v[170:171]
	s_mov_b32 m0, s40
	s_nop 0
	global_load_lds_dwordx4 v[186:187], off
	v_lshl_add_u64 v[186:187], s[24:25], 0, v[154:155]
	s_add_i32 m0, s40, 0x2000
	s_nop 0
	global_load_lds_dwordx4 v[186:187], off
	v_lshl_add_u64 v[234:235], v[234:235], 0, s[44:45]
	v_lshl_add_u64 v[236:237], v[236:237], 0, s[44:45]
	s_waitcnt vmcnt(6)
	s_waitcnt lgkmcnt(0)
	s_barrier
	s_waitcnt lgkmcnt(0)
	v_mfma_f32_16x16x32_bf16 v[70:73], v[14:17], v[190:193], v[70:73]
	v_mfma_f32_16x16x32_bf16 v[54:57], v[14:17], v[210:213], v[54:57]
	v_mfma_f32_16x16x32_bf16 v[38:41], v[14:17], v[218:221], v[38:41]
	v_mfma_f32_16x16x32_bf16 v[0:3], v[14:17], v[226:229], v[0:3]
	v_mfma_f32_16x16x32_bf16 v[70:73], v[22:25], v[194:197], v[70:73]
	v_mfma_f32_16x16x32_bf16 v[62:65], v[138:141], v[190:193], v[62:65]
	v_mfma_f32_16x16x32_bf16 v[54:57], v[22:25], v[214:217], v[54:57]
	s_mov_b32 m0, s38
	v_mfma_f32_16x16x32_bf16 v[46:49], v[138:141], v[210:213], v[46:49]
	global_load_lds_dwordx4 v[234:235], off
	v_mfma_f32_16x16x32_bf16 v[38:41], v[22:25], v[222:225], v[38:41]
	v_mfma_f32_16x16x32_bf16 v[30:33], v[138:141], v[218:221], v[30:33]
	v_mfma_f32_16x16x32_bf16 v[22:25], v[22:25], v[230:233], v[0:3]
	v_mfma_f32_16x16x32_bf16 v[0:3], v[138:141], v[226:229], v[4:7]
	v_mfma_f32_16x16x32_bf16 v[62:65], v[142:145], v[194:197], v[62:65]
	v_mfma_f32_16x16x32_bf16 v[46:49], v[142:145], v[214:217], v[46:49]
	v_mfma_f32_16x16x32_bf16 v[30:33], v[142:145], v[222:225], v[30:33]
	v_mfma_f32_16x16x32_bf16 v[14:17], v[142:145], v[230:233], v[0:3]
	v_mfma_f32_16x16x32_bf16 v[0:3], v[146:149], v[190:193], v[66:69]
	v_mfma_f32_16x16x32_bf16 v[66:69], v[150:153], v[194:197], v[0:3]
	v_mfma_f32_16x16x32_bf16 v[0:3], v[178:181], v[190:193], v[58:61]
	v_mfma_f32_16x16x32_bf16 v[58:61], v[182:185], v[194:197], v[0:3]
	v_mfma_f32_16x16x32_bf16 v[0:3], v[146:149], v[210:213], v[50:53]
	v_mfma_f32_16x16x32_bf16 v[50:53], v[150:153], v[214:217], v[0:3]
	v_mfma_f32_16x16x32_bf16 v[0:3], v[178:181], v[210:213], v[42:45]
	s_mov_b32 m0, s66
	v_mfma_f32_16x16x32_bf16 v[42:45], v[182:185], v[214:217], v[0:3]
	global_load_lds_dwordx4 v[236:237], off
	v_mfma_f32_16x16x32_bf16 v[0:3], v[146:149], v[218:221], v[34:37]
	v_mfma_f32_16x16x32_bf16 v[34:37], v[150:153], v[222:225], v[0:3]
	v_mfma_f32_16x16x32_bf16 v[0:3], v[178:181], v[218:221], v[26:29]
	v_mfma_f32_16x16x32_bf16 v[26:29], v[182:185], v[222:225], v[0:3]
	v_mfma_f32_16x16x32_bf16 v[0:3], v[146:149], v[226:229], v[18:21]
	v_mfma_f32_16x16x32_bf16 v[18:21], v[150:153], v[230:233], v[0:3]
	v_mfma_f32_16x16x32_bf16 v[0:3], v[178:181], v[226:229], v[10:13]
	v_mfma_f32_16x16x32_bf16 v[10:13], v[182:185], v[230:233], v[0:3]
	s_barrier
	s_add_i32 s73, s73, 2
	s_add_u32 s22, s22, 0x100
	s_addc_u32 s23, s23, 0
	s_add_u32 s71, s71, 0x100
	s_addc_u32 s72, s72, 0
	s_cmp_gt_u32 s73, 13
	s_cbranch_scc0 .LBB0_698
	s_and_b64 vcc, exec, s[12:13]
	s_cbranch_vccz .LBB0_701
	s_barrier
